# RG-LRU stage-3 local scan: all eight (a,b) ds_read2 issued up front into free registers and consumed behind counted lgkmcnt waits (was four serial LDS round trips)
# speedup vs baseline: 1.0097x; 1.0097x over previous
; __device__ __forceinline__ float bf2f(bf16_t v) { return __uint_as_float(((unsigned)v) << 16); }
; __device__ __forceinline__ float sigmoidf_(float x) { return __builtin_amdgcn_rcpf(1.f + __expf(-x)); }
; #define MFMA16(a, b, c) __builtin_amdgcn_mfma_f32_16x16x32_bf16((a), (b), (c), 0, 0, 0)
; __device__ __forceinline__ void rglru_unit(const Params& p, const WS& ws, int j, int u, bool dry = false) {
;     ...
;       for (int ks = 0; ks < 4; ++ks) {
;         const bf16x8 xf = *(const bf16x8*)(XC + (16 * w + lr) * 136 + 32 * ks + 8 * lq);
; #pragma unroll
;         for (int gate = 0; gate < 2; ++gate)
; #pragma unroll
;           for (int mt = 0; mt < 2; ++mt) {
;             const bf16x8 wf = *(const bf16x8*)(WG + (gate * 32 + 16 * mt + lr) * 136 + 32 * ks + 8 * lq);
;             ga_[gate][mt] = MFMA16(wf, xf, ga_[gate][mt]);
;           }
;       }
;       const int tok = 16 * w + lr;
; #pragma unroll
;       for (int mt = 0; mt < 2; ++mt)
; #pragma unroll
;         for (int jj = 0; jj < 4; ++jj) {
;           const int n = 16 * mt + 4 * lq + jj;
;           const float xcv = bf2f(XC[tok * 136 + 32 * jq + n]);
;           const float r = sigmoidf_(ga_[0][mt][jj] + ba[mt][jj]);
;           const float ig = sigmoidf_(ga_[1][mt][jj] + bx[mt][jj]);
;           const float la = -r * sp[mt][jj];
;           const float a = __expf(la);
;           const float x2 = 2.f * la;
;           const float om = x2 > -0.02f ? -x2 * (1.f + 0.5f * x2 * (1.f + x2 * (1.f / 3.f))) : 1.f - a * a;
;           const float mult = __builtin_amdgcn_sqrtf(fmaxf(om, 0.f));
;           AUa[tok * 33 + n] = a;
;           AUu[tok * 33 + n] = mult * ig * xcv;
;         }
.LBB0_1420:
	ds_read_b128 v[52:55], v111
	ds_read_b128 v[56:59], v112 offset:17408
	ds_read_b128 v[60:63], v112 offset:21760
	ds_read_b128 v[64:67], v112 offset:26112
	ds_read_b128 v[136:139], v112 offset:30464
	ds_read_b128 v[212:215], v111 offset:64
	ds_read_b128 v[216:219], v111 offset:128
	ds_read_b128 v[220:223], v111 offset:192
	ds_read_b128 v[224:227], v112 offset:17472
	ds_read_b128 v[228:231], v112 offset:21824
	ds_read_b128 v[232:235], v112 offset:26176
	ds_read_b128 v[244:247], v112 offset:30528
	ds_read_b128 v[248:251], v112 offset:17536
	ds_read_b128 v[252:255], v112 offset:21888
	s_waitcnt lgkmcnt(12)
	v_mfma_f32_16x16x32_bf16 v[56:59], v[56:59], v[52:55], 0
	s_waitcnt lgkmcnt(11)
	v_mfma_f32_16x16x32_bf16 v[60:63], v[60:63], v[52:55], 0
	s_waitcnt lgkmcnt(10)
	v_mfma_f32_16x16x32_bf16 v[64:67], v[64:67], v[52:55], 0
	s_waitcnt lgkmcnt(9)
	v_mfma_f32_16x16x32_bf16 v[52:55], v[136:139], v[52:55], 0
	s_nop 0
	s_nop 0
	s_waitcnt lgkmcnt(5)
	v_mfma_f32_16x16x32_bf16 v[56:59], v[224:227], v[212:215], v[56:59]
	ds_read_b128 v[224:227], v112 offset:26240
	s_nop 0
	s_waitcnt lgkmcnt(5)
	v_mfma_f32_16x16x32_bf16 v[60:63], v[228:231], v[212:215], v[60:63]
	ds_read_b128 v[228:231], v112 offset:30592
	s_nop 0
	s_waitcnt lgkmcnt(5)
	v_mfma_f32_16x16x32_bf16 v[64:67], v[232:235], v[212:215], v[64:67]
	ds_read_b128 v[232:235], v112 offset:17600
	s_nop 0
	s_waitcnt lgkmcnt(5)
	v_mfma_f32_16x16x32_bf16 v[52:55], v[244:247], v[212:215], v[52:55]
	ds_read_b128 v[244:247], v112 offset:21952
	s_nop 0
	s_nop 0
	s_waitcnt lgkmcnt(5)
	v_mfma_f32_16x16x32_bf16 v[56:59], v[248:251], v[216:219], v[56:59]
	ds_read_b128 v[248:251], v112 offset:26304
	s_nop 0
	s_waitcnt lgkmcnt(5)
	v_mfma_f32_16x16x32_bf16 v[60:63], v[252:255], v[216:219], v[60:63]
	ds_read_b128 v[252:255], v112 offset:30656
	s_nop 0
	s_waitcnt lgkmcnt(5)
	v_mfma_f32_16x16x32_bf16 v[140:143], v[224:227], v[216:219], v[64:67]
	s_nop 2
	s_nop 0
	s_waitcnt lgkmcnt(4)
	v_mfma_f32_16x16x32_bf16 v[52:55], v[228:231], v[216:219], v[52:55]
	s_nop 0
	s_nop 0
	ds_read_u16 v13, v113
	s_waitcnt lgkmcnt(4)
	v_mfma_f32_16x16x32_bf16 v[64:67], v[232:235], v[220:223], v[56:59]
	s_nop 2
	s_nop 0
	s_waitcnt lgkmcnt(3)
	v_mfma_f32_16x16x32_bf16 v[56:59], v[244:247], v[220:223], v[60:63]
	s_nop 2
	s_nop 0
	v_add_f32_e32 v14, v0, v64
	v_mul_f32_e32 v14, 0xbfb8aa3b, v14
	v_exp_f32_e32 v14, v14
	s_waitcnt lgkmcnt(2)
	v_mfma_f32_16x16x32_bf16 v[60:63], v[248:251], v[220:223], v[140:143]
	s_nop 2
	s_nop 0
	v_add_f32_e32 v14, 1.0, v14
	v_rcp_f32_e64 v14, -v14
	s_waitcnt lgkmcnt(0)
	v_mfma_f32_16x16x32_bf16 v[52:55], v[252:255], v[220:223], v[52:55]
	v_mul_f32_e32 v14, v89, v14
	v_mul_f32_e32 v15, 0x3fb8aa3b, v14
	v_exp_f32_e32 v15, v15
	v_add_f32_e32 v14, v14, v14
	v_cmp_nlt_f32_e64 s[52:53], s29, v14
	s_and_saveexec_b64 s[4:5], s[52:53]
	s_xor_b64 s[4:5], exec, s[4:5]
	v_fma_f32 v64, -v15, v15, 1.0
	s_andn2_saveexec_b64 s[4:5], s[4:5]
	v_pk_mul_f32 v[136:137], v[14:15], s[88:89] op_sel_hi:[0,1]
	v_add_f32_e32 v64, 1.0, v137
	v_fma_f32 v64, v136, v64, 1.0
	v_mul_f32_e64 v64, v64, -v14
	s_or_b64 exec, exec, s[4:5]
	v_add_f32_e32 v14, v8, v60
	v_max_f32_e32 v60, v64, v64
	v_add_f32_e32 v64, v1, v65
	v_mul_f32_e32 v14, 0xbfb8aa3b, v14
	v_mul_f32_e32 v64, 0xbfb8aa3b, v64
	v_exp_f32_e32 v14, v14
	v_exp_f32_e32 v64, v64
	v_max_f32_e32 v60, 0, v60
	v_sqrt_f32_e32 v60, v60
	v_add_f32_e32 v14, 1.0, v14
	v_add_f32_e32 v64, 1.0, v64
	v_rcp_f32_e32 v14, v14
	v_rcp_f32_e64 v64, -v64
	v_lshlrev_b32_e32 v13, 16, v13
	v_mul_f32_e32 v14, v14, v60
	v_mul_f32_e32 v64, v93, v64
	v_mul_f32_e32 v14, v14, v13
	ds_read_u16 v60, v113 offset:2
	v_mul_f32_e32 v13, 0x3fb8aa3b, v64
	v_exp_f32_e32 v13, v13
	ds_write2st64_b32 v72, v15, v14 offset0:136 offset1:169
	v_add_f32_e32 v14, v64, v64
	v_cmp_nlt_f32_e64 s[52:53], s29, v14
	s_and_saveexec_b64 s[4:5], s[52:53]
	s_xor_b64 s[4:5], exec, s[4:5]
	v_fma_f32 v15, -v13, v13, 1.0
	s_andn2_saveexec_b64 s[4:5], s[4:5]
	v_pk_mul_f32 v[64:65], v[14:15], s[88:89] op_sel_hi:[0,1]
	v_add_f32_e32 v15, 1.0, v65
	v_fma_f32 v15, v64, v15, 1.0
	v_mul_f32_e64 v15, v15, -v14
	s_or_b64 exec, exec, s[4:5]
	s_waitcnt lgkmcnt(1)
	v_lshlrev_b32_e32 v14, 16, v60
	v_add_f32_e32 v60, v9, v61
	v_mul_f32_e32 v60, 0xbfb8aa3b, v60
	v_exp_f32_e32 v60, v60
	v_max_f32_e32 v15, v15, v15
	v_max_f32_e32 v15, 0, v15
	v_sqrt_f32_e32 v15, v15
	v_add_f32_e32 v60, 1.0, v60
	v_rcp_f32_e32 v60, v60
	v_add_u32_e32 v135, 4, v72
	v_mul_f32_e32 v15, v60, v15
	v_mul_f32_e32 v14, v15, v14
	ds_write2st64_b32 v135, v13, v14 offset0:136 offset1:169
	v_add_f32_e32 v14, v2, v66
	v_mul_f32_e32 v14, 0xbfb8aa3b, v14
	v_exp_f32_e32 v14, v14
	ds_read_u16 v13, v113 offset:4
	v_add_f32_e32 v14, 1.0, v14
	v_rcp_f32_e64 v14, -v14
	s_nop 0
	v_mul_f32_e32 v14, v95, v14
	v_mul_f32_e32 v15, 0x3fb8aa3b, v14
	v_exp_f32_e32 v15, v15
	v_add_f32_e32 v14, v14, v14
	v_cmp_nlt_f32_e64 s[52:53], s29, v14
	s_and_saveexec_b64 s[4:5], s[52:53]
	s_xor_b64 s[4:5], exec, s[4:5]
	v_fma_f32 v60, -v15, v15, 1.0
	s_andn2_saveexec_b64 s[4:5], s[4:5]
	v_pk_mul_f32 v[60:61], v[14:15], s[88:89] op_sel_hi:[0,1]
	v_add_f32_e32 v61, 1.0, v61
	v_fma_f32 v60, v60, v61, 1.0
	v_mul_f32_e64 v60, v60, -v14
	s_or_b64 exec, exec, s[4:5]
	v_add_f32_e32 v14, v10, v62
	v_mul_f32_e32 v14, 0xbfb8aa3b, v14
	v_exp_f32_e32 v14, v14
	v_max_f32_e32 v60, v60, v60
	v_max_f32_e32 v60, 0, v60
	v_sqrt_f32_e32 v60, v60
	v_add_f32_e32 v14, 1.0, v14
	v_rcp_f32_e32 v14, v14
	s_waitcnt lgkmcnt(0)
; __device__ __forceinline__ float bf2f(bf16_t v) { return __uint_as_float(((unsigned)v) << 16); }
; __device__ __forceinline__ float sigmoidf_(float x) { return __builtin_amdgcn_rcpf(1.f + __expf(-x)); }
; __device__ __forceinline__ void rglru_unit(const Params& p, const WS& ws, int j, int u, bool dry = false) {
;     ...
; #pragma unroll
;       for (int mt = 0; mt < 2; ++mt)
; #pragma unroll
;         for (int jj = 0; jj < 4; ++jj) {
;           const int n = 16 * mt + 4 * lq + jj;
;           const float xcv = bf2f(XC[tok * 136 + 32 * jq + n]);
;           const float r = sigmoidf_(ga_[0][mt][jj] + ba[mt][jj]);
;           const float ig = sigmoidf_(ga_[1][mt][jj] + bx[mt][jj]);
;           const float la = -r * sp[mt][jj];
;           const float a = __expf(la);
;           const float x2 = 2.f * la;
;           const float om = x2 > -0.02f ? -x2 * (1.f + 0.5f * x2 * (1.f + x2 * (1.f / 3.f))) : 1.f - a * a;
;           const float mult = __builtin_amdgcn_sqrtf(fmaxf(om, 0.f));
;           AUa[tok * 33 + n] = a;
;           AUu[tok * 33 + n] = mult * ig * xcv;
;         }
;     }
;     __syncthreads();
	v_lshlrev_b32_e32 v13, 16, v13
	v_add_u32_e32 v136, 8, v72
	v_mul_f32_e32 v14, v14, v60
	v_mul_f32_e32 v13, v14, v13
	v_add_f32_e32 v14, v3, v67
	v_mul_f32_e32 v14, 0xbfb8aa3b, v14
	v_exp_f32_e32 v14, v14
	ds_write2st64_b32 v136, v15, v13 offset0:136 offset1:169
	ds_read_u16 v13, v113 offset:6
	v_add_f32_e32 v14, 1.0, v14
	v_rcp_f32_e64 v14, -v14
	s_nop 0
	v_mul_f32_e32 v14, v96, v14
	v_mul_f32_e32 v15, 0x3fb8aa3b, v14
	v_exp_f32_e32 v15, v15
	v_add_f32_e32 v14, v14, v14
	v_cmp_nlt_f32_e64 s[52:53], s29, v14
	s_and_saveexec_b64 s[4:5], s[52:53]
	s_xor_b64 s[4:5], exec, s[4:5]
	v_fma_f32 v60, -v15, v15, 1.0
	s_andn2_saveexec_b64 s[4:5], s[4:5]
	v_pk_mul_f32 v[60:61], v[14:15], s[88:89] op_sel_hi:[0,1]
	v_add_f32_e32 v61, 1.0, v61
	v_fma_f32 v60, v60, v61, 1.0
	v_mul_f32_e64 v60, v60, -v14
	s_or_b64 exec, exec, s[4:5]
	v_add_f32_e32 v14, v11, v63
	v_mul_f32_e32 v14, 0xbfb8aa3b, v14
	v_exp_f32_e32 v14, v14
	v_max_f32_e32 v60, v60, v60
	v_max_f32_e32 v60, 0, v60
	v_sqrt_f32_e32 v60, v60
	v_add_f32_e32 v14, 1.0, v14
	v_rcp_f32_e32 v14, v14
	s_waitcnt lgkmcnt(0)
	v_lshlrev_b32_e32 v13, 16, v13
	v_add_u32_e32 v139, 12, v72
	v_mul_f32_e32 v14, v14, v60
	v_mul_f32_e32 v13, v14, v13
	v_add_f32_e32 v14, v4, v56
	v_mul_f32_e32 v14, 0xbfb8aa3b, v14
	v_exp_f32_e32 v14, v14
	ds_write2st64_b32 v139, v15, v13 offset0:136 offset1:169
	ds_read_u16 v13, v113 offset:32
	v_add_f32_e32 v14, 1.0, v14
	v_rcp_f32_e64 v14, -v14
	s_nop 0
	v_mul_f32_e32 v14, v97, v14
	v_mul_f32_e32 v15, 0x3fb8aa3b, v14
	v_exp_f32_e32 v15, v15
	v_add_f32_e32 v14, v14, v14
	v_cmp_nlt_f32_e64 s[52:53], s29, v14
	s_and_saveexec_b64 s[4:5], s[52:53]
	s_xor_b64 s[4:5], exec, s[4:5]
	v_fma_f32 v56, -v15, v15, 1.0
	s_andn2_saveexec_b64 s[4:5], s[4:5]
	v_pk_mul_f32 v[60:61], v[14:15], s[88:89] op_sel_hi:[0,1]
	v_add_f32_e32 v56, 1.0, v61
	v_fma_f32 v56, v60, v56, 1.0
	v_mul_f32_e64 v56, v56, -v14
	s_or_b64 exec, exec, s[4:5]
	v_add_f32_e32 v14, v16, v52
	v_mul_f32_e32 v14, 0xbfb8aa3b, v14
	v_exp_f32_e32 v14, v14
	v_max_f32_e32 v52, v56, v56
	v_max_f32_e32 v52, 0, v52
	v_sqrt_f32_e32 v52, v52
	v_add_f32_e32 v14, 1.0, v14
	v_rcp_f32_e32 v14, v14
	s_waitcnt lgkmcnt(0)
	v_lshlrev_b32_e32 v13, 16, v13
	v_add_u32_e32 v141, 64, v72
	v_mul_f32_e32 v14, v14, v52
	v_mul_f32_e32 v13, v14, v13
	v_add_f32_e32 v14, v5, v57
	v_mul_f32_e32 v14, 0xbfb8aa3b, v14
	v_exp_f32_e32 v14, v14
	ds_write2st64_b32 v141, v15, v13 offset0:136 offset1:169
	ds_read_u16 v13, v113 offset:34
	v_add_f32_e32 v14, 1.0, v14
	v_rcp_f32_e64 v14, -v14
	s_nop 0
	v_mul_f32_e32 v14, v98, v14
	v_mul_f32_e32 v15, 0x3fb8aa3b, v14
	v_exp_f32_e32 v15, v15
	v_add_f32_e32 v14, v14, v14
	v_cmp_nlt_f32_e64 s[52:53], s29, v14
	s_and_saveexec_b64 s[4:5], s[52:53]
	s_xor_b64 s[4:5], exec, s[4:5]
	v_fma_f32 v52, -v15, v15, 1.0
	s_andn2_saveexec_b64 s[4:5], s[4:5]
	v_pk_mul_f32 v[56:57], v[14:15], s[88:89] op_sel_hi:[0,1]
	v_add_f32_e32 v52, 1.0, v57
	v_fma_f32 v52, v56, v52, 1.0
	v_mul_f32_e64 v52, v52, -v14
	s_or_b64 exec, exec, s[4:5]
	v_add_f32_e32 v14, v17, v53
	v_mul_f32_e32 v14, 0xbfb8aa3b, v14
	v_exp_f32_e32 v14, v14
	v_max_f32_e32 v52, v52, v52
	v_max_f32_e32 v52, 0, v52
	v_sqrt_f32_e32 v52, v52
	v_add_f32_e32 v14, 1.0, v14
	v_rcp_f32_e32 v14, v14
	s_waitcnt lgkmcnt(0)
	v_lshlrev_b32_e32 v13, 16, v13
	v_add_u32_e32 v142, 0x44, v72
	v_mul_f32_e32 v14, v14, v52
	v_mul_f32_e32 v13, v14, v13
	v_add_f32_e32 v14, v6, v58
	v_mul_f32_e32 v14, 0xbfb8aa3b, v14
	v_exp_f32_e32 v14, v14
	ds_write2st64_b32 v142, v15, v13 offset0:136 offset1:169
	ds_read_u16 v13, v113 offset:36
	v_add_f32_e32 v14, 1.0, v14
	v_rcp_f32_e64 v14, -v14
	s_nop 0
	v_mul_f32_e32 v14, v99, v14
	v_mul_f32_e32 v15, 0x3fb8aa3b, v14
	v_exp_f32_e32 v15, v15
	v_add_f32_e32 v14, v14, v14
	v_cmp_nlt_f32_e64 s[52:53], s29, v14
	s_and_saveexec_b64 s[4:5], s[52:53]
	s_xor_b64 s[4:5], exec, s[4:5]
	v_fma_f32 v52, -v15, v15, 1.0
	s_andn2_saveexec_b64 s[4:5], s[4:5]
	v_pk_mul_f32 v[52:53], v[14:15], s[88:89] op_sel_hi:[0,1]
	v_add_f32_e32 v53, 1.0, v53
	v_fma_f32 v52, v52, v53, 1.0
	v_mul_f32_e64 v52, v52, -v14
	s_or_b64 exec, exec, s[4:5]
	v_add_f32_e32 v14, v18, v54
	v_mul_f32_e32 v14, 0xbfb8aa3b, v14
	v_exp_f32_e32 v14, v14
	v_max_f32_e32 v52, v52, v52
	v_max_f32_e32 v52, 0, v52
	v_sqrt_f32_e32 v52, v52
	v_add_f32_e32 v14, 1.0, v14
	v_rcp_f32_e32 v14, v14
	s_waitcnt lgkmcnt(0)
	v_lshlrev_b32_e32 v13, 16, v13
	v_add_u32_e32 v144, 0x48, v72
	v_mul_f32_e32 v14, v14, v52
	v_mul_f32_e32 v13, v14, v13
	v_add_f32_e32 v14, v7, v59
	v_mul_f32_e32 v14, 0xbfb8aa3b, v14
	v_exp_f32_e32 v14, v14
	ds_write2st64_b32 v144, v15, v13 offset0:136 offset1:169
	ds_read_u16 v13, v113 offset:38
	v_add_f32_e32 v14, 1.0, v14
	v_rcp_f32_e64 v14, -v14
	s_nop 0
	v_mul_f32_e32 v14, v105, v14
	v_mul_f32_e32 v15, 0x3fb8aa3b, v14
	v_exp_f32_e32 v15, v15
	v_add_f32_e32 v14, v14, v14
	v_cmp_nlt_f32_e64 s[52:53], s29, v14
	s_and_saveexec_b64 s[4:5], s[52:53]
	s_xor_b64 s[4:5], exec, s[4:5]
	v_fma_f32 v52, -v15, v15, 1.0
	s_andn2_saveexec_b64 s[4:5], s[4:5]
	v_pk_mul_f32 v[52:53], v[14:15], s[88:89] op_sel_hi:[0,1]
	v_add_f32_e32 v53, 1.0, v53
	v_fma_f32 v52, v52, v53, 1.0
	v_mul_f32_e64 v52, v52, -v14
	s_or_b64 exec, exec, s[4:5]
	v_add_f32_e32 v14, v19, v55
	v_mul_f32_e32 v14, 0xbfb8aa3b, v14
	v_exp_f32_e32 v14, v14
	v_max_f32_e32 v52, v52, v52
	v_max_f32_e32 v52, 0, v52
	v_sqrt_f32_e32 v52, v52
	v_add_f32_e32 v14, 1.0, v14
	v_rcp_f32_e32 v14, v14
	s_waitcnt lgkmcnt(0)
	v_lshlrev_b32_e32 v13, 16, v13
	v_add_u32_e32 v145, 0x4c, v72
	v_add_u32_e32 v137, 0x8800, v114
	v_mul_f32_e32 v14, v14, v52
	v_mul_f32_e32 v13, v14, v13
	v_add_u32_e32 v138, 0xa800, v114
	ds_write2st64_b32 v145, v15, v13 offset0:136 offset1:169
	s_waitcnt lgkmcnt(0)
	s_barrier
; __device__ __forceinline__ void rglru_unit(const Params& p, const WS& ws, int j, int u, bool dry = false) {
;     ...
;     {
;       float A = 1.f, Hh = 0.f;
; #pragma unroll
;       for (int i = 0; i < 8; ++i) {
;         const float a = AUa[(8 * ssg + i) * 33 + sc], uu = AUu[(8 * ssg + i) * 33 + sc];
;         Hh = a * Hh + uu; A *= a;
;       }
;       SEGA[ssg * 32 + sc] = A; SEGH[ssg * 32 + sc] = Hh;
;     }
;     __syncthreads();
;     float hin = CARRY[sc];
; #pragma unroll
;     for (int s2 = 0; s2 < 7; ++s2)
;       if (s2 < ssg) hin = SEGA[s2 * 32 + sc] * hin + SEGH[s2 * 32 + sc];
	ds_read2_b32 v[14:15], v137 offset1:33
	ds_read2_b32 v[52:53], v138 offset0:64 offset1:97
	v_add_u32_e32 v140, 0xac00, v114
	ds_read2_b32 v[204:205], v137 offset0:66 offset1:99
	ds_read2_b32 v[54:55], v138 offset0:130 offset1:163
	ds_read2_b32 v[206:207], v137 offset0:132 offset1:165
	ds_read2_b32 v[244:245], v138 offset0:196 offset1:229
	ds_read2_b32 v[208:209], v137 offset0:198 offset1:231
	ds_read2_b32 v[246:247], v140 offset0:6 offset1:39
	s_waitcnt lgkmcnt(6)
	v_fma_f32 v13, 0, v14, v52
	v_fmac_f32_e32 v53, v13, v15
	v_mul_f32_e32 v13, v14, v15
	s_waitcnt lgkmcnt(4)
	v_mul_f32_e32 v13, v13, v204
	v_fma_f32 v52, v53, v204, v54
	v_fmac_f32_e32 v55, v52, v205
	v_mul_f32_e32 v13, v13, v205
	s_waitcnt lgkmcnt(2)
	v_mul_f32_e32 v13, v13, v206
	v_fma_f32 v244, v55, v206, v244
	v_fmac_f32_e32 v245, v244, v207
	v_mul_f32_e32 v13, v13, v207
	s_waitcnt lgkmcnt(0)
	v_mul_f32_e32 v13, v13, v208
	v_fma_f32 v245, v245, v208, v246
	v_fmac_f32_e32 v247, v245, v209
	v_mul_f32_e32 v13, v13, v209
	ds_write2st64_b32 v78, v13, v247 offset0:202 offset1:206
	s_waitcnt lgkmcnt(0)
	s_barrier
	ds_read_b32 v13, v115 offset:53760
	s_and_saveexec_b64 s[4:5], vcc
	s_cbranch_execz .LBB0_1548
	ds_read2st64_b32 v[14:15], v115 offset0:202 offset1:206
	s_waitcnt lgkmcnt(0)
	v_fmac_f32_e32 v15, v13, v14
	v_mov_b32_e32 v13, v15
	s_or_b64 exec, exec, s[4:5]
	v_add_u32_e32 v143, 0x80, v115
	s_and_saveexec_b64 s[4:5], s[38:39]
	s_cbranch_execnz .LBB0_1549

; __device__ __forceinline__ float bf2f(bf16_t v) { return __uint_as_float(((unsigned)v) << 16); }
; __device__ __forceinline__ float sigmoidf_(float x) { return __builtin_amdgcn_rcpf(1.f + __expf(-x)); }
; #define MFMA16(a, b, c) __builtin_amdgcn_mfma_f32_16x16x32_bf16((a), (b), (c), 0, 0, 0)
; __device__ __forceinline__ void rglru_unit(const Params& p, const WS& ws, int j, int u, bool dry = false) {
;     ...
;       for (int ks = 0; ks < 4; ++ks) {
;         const bf16x8 xf = *(const bf16x8*)(XC + (16 * w + lr) * 136 + 32 * ks + 8 * lq);
; #pragma unroll
;         for (int gate = 0; gate < 2; ++gate)
; #pragma unroll
;           for (int mt = 0; mt < 2; ++mt) {
;             const bf16x8 wf = *(const bf16x8*)(WG + (gate * 32 + 16 * mt + lr) * 136 + 32 * ks + 8 * lq);
;             ga_[gate][mt] = MFMA16(wf, xf, ga_[gate][mt]);
;           }
;       }
;       const int tok = 16 * w + lr;
; #pragma unroll
;       for (int mt = 0; mt < 2; ++mt)
; #pragma unroll
;         for (int jj = 0; jj < 4; ++jj) {
;           const int n = 16 * mt + 4 * lq + jj;
;           const float xcv = bf2f(XC[tok * 136 + 32 * jq + n]);
;           const float r = sigmoidf_(ga_[0][mt][jj] + ba[mt][jj]);
;           const float ig = sigmoidf_(ga_[1][mt][jj] + bx[mt][jj]);
;           const float la = -r * sp[mt][jj];
;           const float a = __expf(la);
;           const float x2 = 2.f * la;
;           const float om = x2 > -0.02f ? -x2 * (1.f + 0.5f * x2 * (1.f + x2 * (1.f / 3.f))) : 1.f - a * a;
;           const float mult = __builtin_amdgcn_sqrtf(fmaxf(om, 0.f));
;           AUa[tok * 33 + n] = a;
;           AUu[tok * 33 + n] = mult * ig * xcv;
;         }
.LBB0_1505:
	ds_read_b128 v[52:55], v111
	ds_read_b128 v[56:59], v112 offset:17408
	ds_read_b128 v[60:63], v112 offset:21760
	ds_read_b128 v[64:67], v112 offset:26112
	ds_read_b128 v[120:123], v112 offset:30464
	ds_read_b128 v[212:215], v111 offset:64
	ds_read_b128 v[216:219], v111 offset:128
	ds_read_b128 v[220:223], v111 offset:192
	ds_read_b128 v[224:227], v112 offset:17472
	ds_read_b128 v[228:231], v112 offset:21824
	ds_read_b128 v[232:235], v112 offset:26176
	ds_read_b128 v[244:247], v112 offset:30528
	ds_read_b128 v[248:251], v112 offset:17536
	ds_read_b128 v[252:255], v112 offset:21888
	s_waitcnt lgkmcnt(12)
	v_mfma_f32_16x16x32_bf16 v[56:59], v[56:59], v[52:55], 0
	s_waitcnt lgkmcnt(11)
	v_mfma_f32_16x16x32_bf16 v[60:63], v[60:63], v[52:55], 0
	s_waitcnt lgkmcnt(10)
	v_mfma_f32_16x16x32_bf16 v[64:67], v[64:67], v[52:55], 0
	s_waitcnt lgkmcnt(9)
	v_mfma_f32_16x16x32_bf16 v[52:55], v[120:123], v[52:55], 0
	s_nop 0
	s_nop 0
	s_waitcnt lgkmcnt(5)
	v_mfma_f32_16x16x32_bf16 v[56:59], v[224:227], v[212:215], v[56:59]
	ds_read_b128 v[224:227], v112 offset:26240
	s_nop 0
	s_waitcnt lgkmcnt(5)
	v_mfma_f32_16x16x32_bf16 v[60:63], v[228:231], v[212:215], v[60:63]
	ds_read_b128 v[228:231], v112 offset:30592
	s_nop 0
	s_waitcnt lgkmcnt(5)
	v_mfma_f32_16x16x32_bf16 v[64:67], v[232:235], v[212:215], v[64:67]
	ds_read_b128 v[232:235], v112 offset:17600
	s_nop 0
	s_waitcnt lgkmcnt(5)
	v_mfma_f32_16x16x32_bf16 v[52:55], v[244:247], v[212:215], v[52:55]
	ds_read_b128 v[244:247], v112 offset:21952
	s_nop 0
	s_nop 0
	s_waitcnt lgkmcnt(5)
	v_mfma_f32_16x16x32_bf16 v[56:59], v[248:251], v[216:219], v[56:59]
	ds_read_b128 v[248:251], v112 offset:26304
	s_nop 0
	s_waitcnt lgkmcnt(5)
	v_mfma_f32_16x16x32_bf16 v[60:63], v[252:255], v[216:219], v[60:63]
	ds_read_b128 v[252:255], v112 offset:30656
	s_nop 0
	s_waitcnt lgkmcnt(5)
	v_mfma_f32_16x16x32_bf16 v[154:157], v[224:227], v[216:219], v[64:67]
	s_nop 2
	s_nop 0
	s_waitcnt lgkmcnt(4)
	v_mfma_f32_16x16x32_bf16 v[52:55], v[228:231], v[216:219], v[52:55]
	s_nop 0
	s_nop 0
	ds_read_u16 v15, v113
	s_waitcnt lgkmcnt(4)
	v_mfma_f32_16x16x32_bf16 v[64:67], v[232:235], v[220:223], v[56:59]
	s_nop 2
	s_nop 0
	s_waitcnt lgkmcnt(3)
	v_mfma_f32_16x16x32_bf16 v[56:59], v[244:247], v[220:223], v[60:63]
	s_nop 2
	s_nop 0
	v_add_f32_e32 v14, v0, v64
	v_mul_f32_e32 v14, 0xbfb8aa3b, v14
	v_exp_f32_e32 v14, v14
	s_waitcnt lgkmcnt(2)
	v_mfma_f32_16x16x32_bf16 v[60:63], v[248:251], v[220:223], v[154:157]
	s_nop 2
	s_nop 0
	v_add_f32_e32 v14, 1.0, v14
	v_rcp_f32_e64 v14, -v14
	s_waitcnt lgkmcnt(0)
	v_mfma_f32_16x16x32_bf16 v[52:55], v[252:255], v[220:223], v[52:55]
	v_mul_f32_e32 v14, v89, v14
	v_mul_f32_e32 v64, 0x3fb8aa3b, v14
	v_exp_f32_e32 v64, v64
	v_add_f32_e32 v14, v14, v14
	v_cmp_nlt_f32_e64 s[52:53], s29, v14
	s_and_saveexec_b64 s[4:5], s[52:53]
	s_xor_b64 s[4:5], exec, s[4:5]
	v_fma_f32 v119, -v64, v64, 1.0
	s_andn2_saveexec_b64 s[4:5], s[4:5]
	v_pk_mul_f32 v[120:121], v[14:15], s[88:89] op_sel_hi:[0,1]
	v_add_f32_e32 v119, 1.0, v121
	v_fma_f32 v119, v120, v119, 1.0
	v_mul_f32_e64 v119, v119, -v14
	s_or_b64 exec, exec, s[4:5]
	v_add_f32_e32 v14, v8, v60
	v_add_f32_e32 v65, v1, v65
	v_mul_f32_e32 v14, 0xbfb8aa3b, v14
	v_mul_f32_e32 v65, 0xbfb8aa3b, v65
	v_exp_f32_e32 v14, v14
	v_exp_f32_e32 v65, v65
	v_max_f32_e32 v60, v119, v119
	v_max_f32_e32 v60, 0, v60
	v_add_f32_e32 v14, 1.0, v14
	v_add_f32_e32 v65, 1.0, v65
	v_rcp_f32_e32 v14, v14
	v_sqrt_f32_e32 v60, v60
	v_rcp_f32_e64 v65, -v65
	v_lshlrev_b32_e32 v15, 16, v15
	v_mul_f32_e32 v14, v14, v60
	v_mul_f32_e32 v65, v93, v65
	v_mul_f32_e32 v14, v14, v15
	ds_read_u16 v60, v113 offset:2
	v_mul_f32_e32 v15, 0x3fb8aa3b, v65
	v_exp_f32_e32 v15, v15
	ds_write2st64_b32 v72, v64, v14 offset0:136 offset1:169
	v_add_f32_e32 v14, v65, v65
	v_cmp_nlt_f32_e64 s[52:53], s29, v14
	s_and_saveexec_b64 s[4:5], s[52:53]
	s_xor_b64 s[4:5], exec, s[4:5]
	v_fma_f32 v64, -v15, v15, 1.0
	s_andn2_saveexec_b64 s[4:5], s[4:5]
	v_pk_mul_f32 v[64:65], v[14:15], s[88:89] op_sel_hi:[0,1]
	v_add_f32_e32 v65, 1.0, v65
	v_fma_f32 v64, v64, v65, 1.0
	v_mul_f32_e64 v64, v64, -v14
	s_or_b64 exec, exec, s[4:5]
	v_add_f32_e32 v14, v9, v61
	v_max_f32_e32 v61, v64, v64
	v_add_f32_e32 v64, v2, v66
	v_mul_f32_e32 v14, 0xbfb8aa3b, v14
	v_mul_f32_e32 v64, 0xbfb8aa3b, v64
	v_exp_f32_e32 v14, v14
	v_exp_f32_e32 v64, v64
	v_max_f32_e32 v61, 0, v61
	v_sqrt_f32_e32 v61, v61
	v_add_f32_e32 v14, 1.0, v14
	v_add_f32_e32 v64, 1.0, v64
	v_rcp_f32_e32 v14, v14
	v_rcp_f32_e64 v64, -v64
	s_waitcnt lgkmcnt(1)
	v_lshlrev_b32_e32 v60, 16, v60
	v_mul_f32_e32 v14, v14, v61
	v_mul_f32_e32 v64, v95, v64
	v_mul_f32_e32 v14, v14, v60
	ds_read_u16 v61, v113 offset:4
	v_mul_f32_e32 v60, 0x3fb8aa3b, v64
	v_exp_f32_e32 v60, v60
	ds_write2st64_b32 v135, v15, v14 offset0:136 offset1:169
	v_add_f32_e32 v14, v64, v64
	v_cmp_nlt_f32_e64 s[52:53], s29, v14
	s_and_saveexec_b64 s[4:5], s[52:53]
	s_xor_b64 s[4:5], exec, s[4:5]
	v_fma_f32 v15, -v60, v60, 1.0
	s_andn2_saveexec_b64 s[4:5], s[4:5]
	v_pk_mul_f32 v[64:65], v[14:15], s[88:89] op_sel_hi:[0,1]
	v_add_f32_e32 v15, 1.0, v65
	v_fma_f32 v15, v64, v15, 1.0
	v_mul_f32_e64 v15, v15, -v14
	s_or_b64 exec, exec, s[4:5]
	v_add_f32_e32 v14, v10, v62
	v_add_f32_e32 v62, v3, v67
	v_mul_f32_e32 v14, 0xbfb8aa3b, v14
	v_mul_f32_e32 v62, 0xbfb8aa3b, v62
	v_exp_f32_e32 v14, v14
	v_exp_f32_e32 v62, v62
	v_max_f32_e32 v15, v15, v15
	v_max_f32_e32 v15, 0, v15
	v_add_f32_e32 v14, 1.0, v14
	v_add_f32_e32 v62, 1.0, v62
	v_rcp_f32_e32 v14, v14
	v_sqrt_f32_e32 v15, v15
	v_rcp_f32_e64 v62, -v62
	s_waitcnt lgkmcnt(1)
; __device__ __forceinline__ float bf2f(bf16_t v) { return __uint_as_float(((unsigned)v) << 16); }
; __device__ __forceinline__ float sigmoidf_(float x) { return __builtin_amdgcn_rcpf(1.f + __expf(-x)); }
; __device__ __forceinline__ void rglru_unit(const Params& p, const WS& ws, int j, int u, bool dry = false) {
;     ...
; #pragma unroll
;       for (int mt = 0; mt < 2; ++mt)
; #pragma unroll
;         for (int jj = 0; jj < 4; ++jj) {
;           const int n = 16 * mt + 4 * lq + jj;
;           const float xcv = bf2f(XC[tok * 136 + 32 * jq + n]);
;           const float r = sigmoidf_(ga_[0][mt][jj] + ba[mt][jj]);
;           const float ig = sigmoidf_(ga_[1][mt][jj] + bx[mt][jj]);
;           const float la = -r * sp[mt][jj];
;           const float a = __expf(la);
;           const float x2 = 2.f * la;
;           const float om = x2 > -0.02f ? -x2 * (1.f + 0.5f * x2 * (1.f + x2 * (1.f / 3.f))) : 1.f - a * a;
;           const float mult = __builtin_amdgcn_sqrtf(fmaxf(om, 0.f));
;           AUa[tok * 33 + n] = a;
;           AUu[tok * 33 + n] = mult * ig * xcv;
;         }
;     }
;     __syncthreads();
;     {
;       float A = 1.f, Hh = 0.f;
; #pragma unroll
;       for (int i = 0; i < 8; ++i) {
;         const float a = AUa[(8 * ssg + i) * 33 + sc], uu = AUu[(8 * ssg + i) * 33 + sc];
;         Hh = a * Hh + uu; A *= a;
;       }
;       SEGA[ssg * 32 + sc] = A; SEGH[ssg * 32 + sc] = Hh;
;     }
;     __syncthreads();
;     float hin = CARRY[sc];
; #pragma unroll
;     for (int s2 = 0; s2 < 7; ++s2)
;       if (s2 < ssg) hin = SEGA[s2 * 32 + sc] * hin + SEGH[s2 * 32 + sc];
	v_lshlrev_b32_e32 v61, 16, v61
	v_mul_f32_e32 v14, v14, v15
	v_mul_f32_e32 v62, v96, v62
	v_mul_f32_e32 v14, v14, v61
	ds_read_u16 v61, v113 offset:6
	v_mul_f32_e32 v15, 0x3fb8aa3b, v62
	v_exp_f32_e32 v15, v15
	ds_write2st64_b32 v136, v60, v14 offset0:136 offset1:169
	v_add_f32_e32 v14, v62, v62
	v_cmp_nlt_f32_e64 s[52:53], s29, v14
	s_and_saveexec_b64 s[4:5], s[52:53]
	s_xor_b64 s[4:5], exec, s[4:5]
	v_fma_f32 v60, -v15, v15, 1.0
	s_andn2_saveexec_b64 s[4:5], s[4:5]
	v_pk_mul_f32 v[64:65], v[14:15], s[88:89] op_sel_hi:[0,1]
	v_add_f32_e32 v60, 1.0, v65
	v_fma_f32 v60, v64, v60, 1.0
	v_mul_f32_e64 v60, v60, -v14
	s_or_b64 exec, exec, s[4:5]
	v_add_f32_e32 v14, v11, v63
	v_mul_f32_e32 v14, 0xbfb8aa3b, v14
	v_add_f32_e32 v56, v4, v56
	v_exp_f32_e32 v14, v14
	v_mul_f32_e32 v56, 0xbfb8aa3b, v56
	v_exp_f32_e32 v56, v56
	v_max_f32_e32 v60, v60, v60
	v_add_f32_e32 v14, 1.0, v14
	v_max_f32_e32 v60, 0, v60
	v_rcp_f32_e32 v14, v14
	v_sqrt_f32_e32 v60, v60
	v_add_f32_e32 v56, 1.0, v56
	v_rcp_f32_e64 v56, -v56
	s_waitcnt lgkmcnt(1)
	v_lshlrev_b32_e32 v61, 16, v61
	v_mul_f32_e32 v14, v14, v60
	v_mul_f32_e32 v14, v14, v61
	v_mul_f32_e32 v61, v97, v56
	ds_read_u16 v60, v113 offset:32
	v_mul_f32_e32 v56, 0x3fb8aa3b, v61
	v_exp_f32_e32 v56, v56
	ds_write2st64_b32 v139, v15, v14 offset0:136 offset1:169
	v_add_f32_e32 v14, v61, v61
	v_cmp_nlt_f32_e64 s[52:53], s29, v14
	s_and_saveexec_b64 s[4:5], s[52:53]
	s_xor_b64 s[4:5], exec, s[4:5]
	v_fma_f32 v15, -v56, v56, 1.0
	s_andn2_saveexec_b64 s[4:5], s[4:5]
	v_pk_mul_f32 v[62:63], v[14:15], s[88:89] op_sel_hi:[0,1]
	v_add_f32_e32 v15, 1.0, v63
	v_fma_f32 v15, v62, v15, 1.0
	v_mul_f32_e64 v15, v15, -v14
	s_or_b64 exec, exec, s[4:5]
	v_add_f32_e32 v14, v16, v52
	v_mul_f32_e32 v14, 0xbfb8aa3b, v14
	v_add_f32_e32 v52, v5, v57
	v_exp_f32_e32 v14, v14
	v_mul_f32_e32 v52, 0xbfb8aa3b, v52
	v_exp_f32_e32 v52, v52
	v_max_f32_e32 v15, v15, v15
	v_add_f32_e32 v14, 1.0, v14
	v_max_f32_e32 v15, 0, v15
	v_rcp_f32_e32 v14, v14
	v_sqrt_f32_e32 v15, v15
	v_add_f32_e32 v52, 1.0, v52
	s_waitcnt lgkmcnt(1)
	v_lshlrev_b32_e32 v57, 16, v60
	v_rcp_f32_e64 v60, -v52
	v_mul_f32_e32 v14, v14, v15
	v_mul_f32_e32 v14, v14, v57
	ds_read_u16 v52, v113 offset:34
	v_mul_f32_e32 v57, v98, v60
	v_mul_f32_e32 v15, 0x3fb8aa3b, v57
	v_exp_f32_e32 v15, v15
	ds_write2st64_b32 v141, v56, v14 offset0:136 offset1:169
	v_add_f32_e32 v14, v57, v57
	v_cmp_nlt_f32_e64 s[52:53], s29, v14
	s_and_saveexec_b64 s[4:5], s[52:53]
	s_xor_b64 s[4:5], exec, s[4:5]
	v_fma_f32 v56, -v15, v15, 1.0
	s_andn2_saveexec_b64 s[4:5], s[4:5]
	v_pk_mul_f32 v[56:57], v[14:15], s[88:89] op_sel_hi:[0,1]
	v_add_f32_e32 v57, 1.0, v57
	v_fma_f32 v56, v56, v57, 1.0
	v_mul_f32_e64 v56, v56, -v14
	s_or_b64 exec, exec, s[4:5]
	v_add_f32_e32 v14, v17, v53
	v_max_f32_e32 v53, v56, v56
	v_add_f32_e32 v56, v6, v58
	v_mul_f32_e32 v14, 0xbfb8aa3b, v14
	v_mul_f32_e32 v56, 0xbfb8aa3b, v56
	v_exp_f32_e32 v14, v14
	v_exp_f32_e32 v56, v56
	v_max_f32_e32 v53, 0, v53
	v_sqrt_f32_e32 v53, v53
	v_add_f32_e32 v14, 1.0, v14
	v_add_f32_e32 v56, 1.0, v56
	v_rcp_f32_e32 v14, v14
	v_rcp_f32_e64 v56, -v56
	s_waitcnt lgkmcnt(1)
	v_lshlrev_b32_e32 v52, 16, v52
	v_mul_f32_e32 v14, v14, v53
	v_mul_f32_e32 v56, v99, v56
	v_mul_f32_e32 v14, v14, v52
	ds_read_u16 v53, v113 offset:36
	v_mul_f32_e32 v52, 0x3fb8aa3b, v56
	v_exp_f32_e32 v52, v52
	ds_write2st64_b32 v142, v15, v14 offset0:136 offset1:169
	v_add_f32_e32 v14, v56, v56
	v_cmp_nlt_f32_e64 s[52:53], s29, v14
	s_and_saveexec_b64 s[4:5], s[52:53]
	s_xor_b64 s[4:5], exec, s[4:5]
	v_fma_f32 v15, -v52, v52, 1.0
	s_andn2_saveexec_b64 s[4:5], s[4:5]
	v_pk_mul_f32 v[56:57], v[14:15], s[88:89] op_sel_hi:[0,1]
	v_add_f32_e32 v15, 1.0, v57
	v_fma_f32 v15, v56, v15, 1.0
	v_mul_f32_e64 v15, v15, -v14
	s_or_b64 exec, exec, s[4:5]
	v_add_f32_e32 v14, v18, v54
	v_add_f32_e32 v54, v7, v59
	v_mul_f32_e32 v14, 0xbfb8aa3b, v14
	v_mul_f32_e32 v54, 0xbfb8aa3b, v54
	v_exp_f32_e32 v14, v14
	v_exp_f32_e32 v54, v54
	v_max_f32_e32 v15, v15, v15
	v_max_f32_e32 v15, 0, v15
	v_add_f32_e32 v14, 1.0, v14
	v_add_f32_e32 v54, 1.0, v54
	v_rcp_f32_e32 v14, v14
	v_sqrt_f32_e32 v15, v15
	v_rcp_f32_e64 v54, -v54
	s_waitcnt lgkmcnt(1)
	v_lshlrev_b32_e32 v53, 16, v53
	v_mul_f32_e32 v14, v14, v15
	v_mul_f32_e32 v54, v105, v54
	v_mul_f32_e32 v14, v14, v53
	ds_read_u16 v53, v113 offset:38
	v_mul_f32_e32 v15, 0x3fb8aa3b, v54
	v_exp_f32_e32 v15, v15
	ds_write2st64_b32 v144, v52, v14 offset0:136 offset1:169
	v_add_f32_e32 v14, v54, v54
	v_cmp_nlt_f32_e64 s[52:53], s29, v14
	s_and_saveexec_b64 s[4:5], s[52:53]
	s_xor_b64 s[4:5], exec, s[4:5]
	v_fma_f32 v52, -v15, v15, 1.0
	s_andn2_saveexec_b64 s[4:5], s[4:5]
	v_pk_mul_f32 v[56:57], v[14:15], s[88:89] op_sel_hi:[0,1]
	v_add_f32_e32 v52, 1.0, v57
	v_fma_f32 v52, v56, v52, 1.0
	v_mul_f32_e64 v52, v52, -v14
	s_or_b64 exec, exec, s[4:5]
	s_waitcnt lgkmcnt(1)
	v_lshlrev_b32_e32 v14, 16, v53
	v_add_f32_e32 v53, v19, v55
	v_mul_f32_e32 v53, 0xbfb8aa3b, v53
	v_exp_f32_e32 v53, v53
	v_max_f32_e32 v52, v52, v52
	v_max_f32_e32 v52, 0, v52
	v_sqrt_f32_e32 v52, v52
	v_add_f32_e32 v53, 1.0, v53
	v_rcp_f32_e32 v53, v53
	s_nop 0
	v_mul_f32_e32 v52, v53, v52
	v_mul_f32_e32 v14, v52, v14
	ds_write2st64_b32 v145, v15, v14 offset0:136 offset1:169
	s_waitcnt lgkmcnt(0)
	s_barrier
	ds_read2_b32 v[14:15], v137 offset1:33
	ds_read2_b32 v[52:53], v138 offset0:64 offset1:97
	s_nop 0
	ds_read2_b32 v[204:205], v137 offset0:66 offset1:99
	ds_read2_b32 v[54:55], v138 offset0:130 offset1:163
	ds_read2_b32 v[206:207], v137 offset0:132 offset1:165
	ds_read2_b32 v[244:245], v138 offset0:196 offset1:229
	ds_read2_b32 v[208:209], v137 offset0:198 offset1:231
	ds_read2_b32 v[246:247], v140 offset0:6 offset1:39
	s_waitcnt lgkmcnt(6)
	v_fma_f32 v52, 0, v14, v52
	v_fmac_f32_e32 v53, v52, v15
	v_mul_f32_e32 v52, v14, v15
	s_waitcnt lgkmcnt(4)
	v_fma_f32 v53, v53, v204, v54
	v_mul_f32_e32 v14, v52, v204
	v_fmac_f32_e32 v55, v53, v205
	v_mul_f32_e32 v54, v14, v205
	s_waitcnt lgkmcnt(2)
	v_fma_f32 v244, v55, v206, v244
	v_mul_f32_e32 v14, v54, v206
	v_fmac_f32_e32 v245, v244, v207
	v_mul_f32_e32 v52, v14, v207
	s_waitcnt lgkmcnt(0)
	v_fma_f32 v245, v245, v208, v246
	v_mul_f32_e32 v14, v52, v208
	v_fmac_f32_e32 v247, v245, v209
	v_mul_f32_e32 v14, v14, v209
	ds_write2st64_b32 v78, v14, v247 offset0:202 offset1:206
	s_waitcnt lgkmcnt(0)
	s_barrier
	ds_read_b32 v14, v115 offset:53760
	s_and_saveexec_b64 s[4:5], vcc
	s_cbranch_execz .LBB0_1557
	ds_read2st64_b32 v[52:53], v115 offset0:202 offset1:206
	s_waitcnt lgkmcnt(0)
	v_fmac_f32_e32 v53, v14, v52
	v_mov_b32_e32 v14, v53
	s_or_b64 exec, exec, s[4:5]
	s_and_saveexec_b64 s[4:5], s[38:39]
	s_cbranch_execnz .LBB0_1558
